# phase0 modulation dot-product loop: rolling prefetch of the 8 weight-row loads (last iteration peeled)
# speedup vs baseline: 1.0352x; 1.0050x over previous
.LBB0_393:
	s_andn2_b64 vcc, exec, s[0:1]
	s_cbranch_vccnz .LBB0_353
	s_mov_b64 s[0:1], 0
	global_load_dword v152, v213, s[92:93]
	global_load_dword v153, v213, s[92:93] offset:1024
	global_load_dword v154, v213, s[92:93] offset:2048
	global_load_dword v155, v213, s[92:93] offset:3072
	v_mov_b32_e32 v254, v213
	global_load_dword v156, v254, s[90:91]
	global_load_dword v157, v254, s[90:91] offset:1024
	global_load_dword v158, v254, s[90:91] offset:2048
	global_load_dword v159, v254, s[90:91] offset:3072
	v_add_u32_e32 v254, 0x1000, v213
	global_load_dword v160, v254, s[90:91]
	global_load_dword v161, v254, s[90:91] offset:1024
	global_load_dword v162, v254, s[90:91] offset:2048
	global_load_dword v163, v254, s[90:91] offset:3072
	v_add_u32_e32 v254, 0x2000, v213
	global_load_dword v164, v254, s[90:91]
	global_load_dword v165, v254, s[90:91] offset:1024
	global_load_dword v166, v254, s[90:91] offset:2048
	global_load_dword v167, v254, s[90:91] offset:3072
	v_add_u32_e32 v254, 0x3000, v213
	global_load_dword v168, v254, s[90:91]
	global_load_dword v169, v254, s[90:91] offset:1024
	global_load_dword v170, v254, s[90:91] offset:2048
	global_load_dword v171, v254, s[90:91] offset:3072
	v_add_u32_e32 v254, 0x4000, v213
	global_load_dword v233, v254, s[90:91]
	global_load_dword v234, v254, s[90:91] offset:1024
	global_load_dword v235, v254, s[90:91] offset:2048
	global_load_dword v236, v254, s[90:91] offset:3072
	v_add_u32_e32 v254, 0x5000, v213
	global_load_dword v237, v254, s[90:91]
	global_load_dword v238, v254, s[90:91] offset:1024
	global_load_dword v239, v254, s[90:91] offset:2048
	global_load_dword v240, v254, s[90:91] offset:3072
	v_add_u32_e32 v254, 0x6000, v213
	global_load_dword v241, v254, s[90:91]
	global_load_dword v242, v254, s[90:91] offset:1024
	global_load_dword v243, v254, s[90:91] offset:2048
	global_load_dword v244, v254, s[90:91] offset:3072
	v_add_u32_e32 v254, 0x7000, v213
	global_load_dword v249, v254, s[90:91]
	global_load_dword v250, v254, s[90:91] offset:1024
	global_load_dword v251, v254, s[90:91] offset:2048
	global_load_dword v252, v254, s[90:91] offset:3072
	s_waitcnt vmcnt(35)
	v_mul_f32_e32 v253, 0xbfb8aa3b, v152
	v_exp_f32_e32 v253, v253
	s_nop 0
	v_add_f32_e32 v253, 1.0, v253
	v_rcp_f32_e32 v253, v253
	s_nop 0
	v_mul_f32_e32 v152, v152, v253
	ds_write_b32 v213, v152
	s_waitcnt vmcnt(34)
	v_mul_f32_e32 v253, 0xbfb8aa3b, v153
	v_exp_f32_e32 v253, v253
	s_nop 0
	v_add_f32_e32 v253, 1.0, v253
	v_rcp_f32_e32 v253, v253
	s_nop 0
	v_mul_f32_e32 v153, v153, v253
	ds_write_b32 v213, v153 offset:1024
	s_waitcnt vmcnt(33)
	v_mul_f32_e32 v253, 0xbfb8aa3b, v154
	v_exp_f32_e32 v253, v253
	s_nop 0
	v_add_f32_e32 v253, 1.0, v253
	v_rcp_f32_e32 v253, v253
	s_nop 0
	v_mul_f32_e32 v154, v154, v253
	ds_write_b32 v213, v154 offset:2048
	s_waitcnt vmcnt(32)
	v_mul_f32_e32 v253, 0xbfb8aa3b, v155
	v_exp_f32_e32 v253, v253
	s_nop 0
	v_add_f32_e32 v253, 1.0, v253
	v_rcp_f32_e32 v253, v253
	s_nop 0
	v_mul_f32_e32 v155, v155, v253
	ds_write_b32 v213, v155 offset:3072
	s_waitcnt vmcnt(31)
	v_mul_f32_e32 v253, 0xbfb8aa3b, v156
	v_exp_f32_e32 v253, v253
	s_nop 0
	v_add_f32_e32 v253, 1.0, v253
	v_rcp_f32_e32 v253, v253
	s_nop 0
	v_mul_f32_e32 v156, v156, v253
	ds_write_b32 v213, v156 offset:4096
	s_waitcnt vmcnt(30)
	v_mul_f32_e32 v253, 0xbfb8aa3b, v157
	v_exp_f32_e32 v253, v253
	s_nop 0
	v_add_f32_e32 v253, 1.0, v253
	v_rcp_f32_e32 v253, v253
	s_nop 0
	v_mul_f32_e32 v157, v157, v253
	ds_write_b32 v213, v157 offset:5120
	s_waitcnt vmcnt(29)
	v_mul_f32_e32 v253, 0xbfb8aa3b, v158
	v_exp_f32_e32 v253, v253
	s_nop 0
	v_add_f32_e32 v253, 1.0, v253
	v_rcp_f32_e32 v253, v253
	s_nop 0
	v_mul_f32_e32 v158, v158, v253
	ds_write_b32 v213, v158 offset:6144
	s_waitcnt vmcnt(28)
	v_mul_f32_e32 v253, 0xbfb8aa3b, v159
	v_exp_f32_e32 v253, v253
	s_nop 0
	v_add_f32_e32 v253, 1.0, v253
	v_rcp_f32_e32 v253, v253
	s_nop 0
	v_mul_f32_e32 v159, v159, v253
	ds_write_b32 v213, v159 offset:7168
	s_waitcnt vmcnt(27)
	v_mul_f32_e32 v253, 0xbfb8aa3b, v160
	v_exp_f32_e32 v253, v253
	s_nop 0
	v_add_f32_e32 v253, 1.0, v253
	v_rcp_f32_e32 v253, v253
	s_nop 0
	v_mul_f32_e32 v160, v160, v253
	ds_write_b32 v213, v160 offset:8192
	s_waitcnt vmcnt(26)
	v_mul_f32_e32 v253, 0xbfb8aa3b, v161
	v_exp_f32_e32 v253, v253
	s_nop 0
	v_add_f32_e32 v253, 1.0, v253
	v_rcp_f32_e32 v253, v253
	s_nop 0
	v_mul_f32_e32 v161, v161, v253
	ds_write_b32 v213, v161 offset:9216
	s_waitcnt vmcnt(25)
	v_mul_f32_e32 v253, 0xbfb8aa3b, v162
	v_exp_f32_e32 v253, v253
	s_nop 0
	v_add_f32_e32 v253, 1.0, v253
	v_rcp_f32_e32 v253, v253
	s_nop 0
	v_mul_f32_e32 v162, v162, v253
	ds_write_b32 v213, v162 offset:10240
	s_waitcnt vmcnt(24)
	v_mul_f32_e32 v253, 0xbfb8aa3b, v163
	v_exp_f32_e32 v253, v253
	s_nop 0
	v_add_f32_e32 v253, 1.0, v253
	v_rcp_f32_e32 v253, v253
	s_nop 0
	v_mul_f32_e32 v163, v163, v253
	ds_write_b32 v213, v163 offset:11264
	s_waitcnt vmcnt(23)
	v_mul_f32_e32 v253, 0xbfb8aa3b, v164
	v_exp_f32_e32 v253, v253
	s_nop 0
	v_add_f32_e32 v253, 1.0, v253
	v_rcp_f32_e32 v253, v253
	s_nop 0
	v_mul_f32_e32 v164, v164, v253
	ds_write_b32 v213, v164 offset:12288
	s_waitcnt vmcnt(22)
	v_mul_f32_e32 v253, 0xbfb8aa3b, v165
	v_exp_f32_e32 v253, v253
	s_nop 0
	v_add_f32_e32 v253, 1.0, v253
	v_rcp_f32_e32 v253, v253
	s_nop 0
	v_mul_f32_e32 v165, v165, v253
	ds_write_b32 v213, v165 offset:13312
	s_waitcnt vmcnt(21)
	v_mul_f32_e32 v253, 0xbfb8aa3b, v166
	v_exp_f32_e32 v253, v253
	s_nop 0
	v_add_f32_e32 v253, 1.0, v253
	v_rcp_f32_e32 v253, v253
	s_nop 0
	v_mul_f32_e32 v166, v166, v253
	ds_write_b32 v213, v166 offset:14336
	s_waitcnt vmcnt(20)
	v_mul_f32_e32 v253, 0xbfb8aa3b, v167
	v_exp_f32_e32 v253, v253
	s_nop 0
	v_add_f32_e32 v253, 1.0, v253
	v_rcp_f32_e32 v253, v253
	s_nop 0
	v_mul_f32_e32 v167, v167, v253
	ds_write_b32 v213, v167 offset:15360
	s_waitcnt vmcnt(19)
	v_mul_f32_e32 v253, 0xbfb8aa3b, v168
	v_exp_f32_e32 v253, v253
	s_nop 0
	v_add_f32_e32 v253, 1.0, v253
	v_rcp_f32_e32 v253, v253
	s_nop 0
	v_mul_f32_e32 v168, v168, v253
	ds_write_b32 v213, v168 offset:16384
	s_waitcnt vmcnt(18)
	v_mul_f32_e32 v253, 0xbfb8aa3b, v169
	v_exp_f32_e32 v253, v253
	s_nop 0
	v_add_f32_e32 v253, 1.0, v253
	v_rcp_f32_e32 v253, v253
	s_nop 0
	v_mul_f32_e32 v169, v169, v253
	ds_write_b32 v213, v169 offset:17408
	s_waitcnt vmcnt(17)
	v_mul_f32_e32 v253, 0xbfb8aa3b, v170
	v_exp_f32_e32 v253, v253
	s_nop 0
	v_add_f32_e32 v253, 1.0, v253
	v_rcp_f32_e32 v253, v253
	s_nop 0
	v_mul_f32_e32 v170, v170, v253
	ds_write_b32 v213, v170 offset:18432
	s_waitcnt vmcnt(16)
	v_mul_f32_e32 v253, 0xbfb8aa3b, v171
	v_exp_f32_e32 v253, v253
	s_nop 0
	v_add_f32_e32 v253, 1.0, v253
	v_rcp_f32_e32 v253, v253
	s_nop 0
	v_mul_f32_e32 v171, v171, v253
	ds_write_b32 v213, v171 offset:19456
	s_waitcnt vmcnt(15)
	v_mul_f32_e32 v253, 0xbfb8aa3b, v233
	v_exp_f32_e32 v253, v253
	s_nop 0
	v_add_f32_e32 v253, 1.0, v253
	v_rcp_f32_e32 v253, v253
	s_nop 0
	v_mul_f32_e32 v233, v233, v253
	ds_write_b32 v213, v233 offset:20480
	s_waitcnt vmcnt(14)
	v_mul_f32_e32 v253, 0xbfb8aa3b, v234
	v_exp_f32_e32 v253, v253
	s_nop 0
	v_add_f32_e32 v253, 1.0, v253
	v_rcp_f32_e32 v253, v253
	s_nop 0
	v_mul_f32_e32 v234, v234, v253
	ds_write_b32 v213, v234 offset:21504
	s_waitcnt vmcnt(13)
	v_mul_f32_e32 v253, 0xbfb8aa3b, v235
	v_exp_f32_e32 v253, v253
	s_nop 0
	v_add_f32_e32 v253, 1.0, v253
	v_rcp_f32_e32 v253, v253
	s_nop 0
	v_mul_f32_e32 v235, v235, v253
	ds_write_b32 v213, v235 offset:22528
	s_waitcnt vmcnt(12)
	v_mul_f32_e32 v253, 0xbfb8aa3b, v236
	v_exp_f32_e32 v253, v253
	s_nop 0
	v_add_f32_e32 v253, 1.0, v253
	v_rcp_f32_e32 v253, v253
	s_nop 0
	v_mul_f32_e32 v236, v236, v253
	ds_write_b32 v213, v236 offset:23552
	s_waitcnt vmcnt(11)
	v_mul_f32_e32 v253, 0xbfb8aa3b, v237
	v_exp_f32_e32 v253, v253
	s_nop 0
	v_add_f32_e32 v253, 1.0, v253
	v_rcp_f32_e32 v253, v253
	s_nop 0
	v_mul_f32_e32 v237, v237, v253
	ds_write_b32 v213, v237 offset:24576
	s_waitcnt vmcnt(10)
	v_mul_f32_e32 v253, 0xbfb8aa3b, v238
	v_exp_f32_e32 v253, v253
	s_nop 0
	v_add_f32_e32 v253, 1.0, v253
	v_rcp_f32_e32 v253, v253
	s_nop 0
	v_mul_f32_e32 v238, v238, v253
	ds_write_b32 v213, v238 offset:25600
	s_waitcnt vmcnt(9)
	v_mul_f32_e32 v253, 0xbfb8aa3b, v239
	v_exp_f32_e32 v253, v253
	s_nop 0
	v_add_f32_e32 v253, 1.0, v253
	v_rcp_f32_e32 v253, v253
	s_nop 0
	v_mul_f32_e32 v239, v239, v253
	ds_write_b32 v213, v239 offset:26624
	s_waitcnt vmcnt(8)
	v_mul_f32_e32 v253, 0xbfb8aa3b, v240
	v_exp_f32_e32 v253, v253
	s_nop 0
	v_add_f32_e32 v253, 1.0, v253
	v_rcp_f32_e32 v253, v253
	s_nop 0
	v_mul_f32_e32 v240, v240, v253
	ds_write_b32 v213, v240 offset:27648
	s_waitcnt vmcnt(7)
	v_mul_f32_e32 v253, 0xbfb8aa3b, v241
	v_exp_f32_e32 v253, v253
	s_nop 0
	v_add_f32_e32 v253, 1.0, v253
	v_rcp_f32_e32 v253, v253
	s_nop 0
	v_mul_f32_e32 v241, v241, v253
	ds_write_b32 v213, v241 offset:28672
	s_waitcnt vmcnt(6)
	v_mul_f32_e32 v253, 0xbfb8aa3b, v242
	v_exp_f32_e32 v253, v253
	s_nop 0
	v_add_f32_e32 v253, 1.0, v253
	v_rcp_f32_e32 v253, v253
	s_nop 0
	v_mul_f32_e32 v242, v242, v253
	ds_write_b32 v213, v242 offset:29696
	s_waitcnt vmcnt(5)
	v_mul_f32_e32 v253, 0xbfb8aa3b, v243
	v_exp_f32_e32 v253, v253
	s_nop 0
	v_add_f32_e32 v253, 1.0, v253
	v_rcp_f32_e32 v253, v253
	s_nop 0
	v_mul_f32_e32 v243, v243, v253
	ds_write_b32 v213, v243 offset:30720
	s_waitcnt vmcnt(4)
	v_mul_f32_e32 v253, 0xbfb8aa3b, v244
	v_exp_f32_e32 v253, v253
	s_nop 0
	v_add_f32_e32 v253, 1.0, v253
	v_rcp_f32_e32 v253, v253
	s_nop 0
	v_mul_f32_e32 v244, v244, v253
	ds_write_b32 v213, v244 offset:31744
	s_waitcnt vmcnt(3)
	v_mul_f32_e32 v253, 0xbfb8aa3b, v249
	v_exp_f32_e32 v253, v253
	s_nop 0
	v_add_f32_e32 v253, 1.0, v253
	v_rcp_f32_e32 v253, v253
	s_nop 0
	v_mul_f32_e32 v249, v249, v253
	ds_write_b32 v213, v249 offset:32768
	s_waitcnt vmcnt(2)
	v_mul_f32_e32 v253, 0xbfb8aa3b, v250
	v_exp_f32_e32 v253, v253
	s_nop 0
	v_add_f32_e32 v253, 1.0, v253
	v_rcp_f32_e32 v253, v253
	s_nop 0
	v_mul_f32_e32 v250, v250, v253
	ds_write_b32 v213, v250 offset:33792
	s_waitcnt vmcnt(1)
	v_mul_f32_e32 v253, 0xbfb8aa3b, v251
	v_exp_f32_e32 v253, v253
	s_nop 0
	v_add_f32_e32 v253, 1.0, v253
	v_rcp_f32_e32 v253, v253
	s_nop 0
	v_mul_f32_e32 v251, v251, v253
	ds_write_b32 v213, v251 offset:34816
	s_waitcnt vmcnt(0)
	v_mul_f32_e32 v253, 0xbfb8aa3b, v252
	v_exp_f32_e32 v253, v253
	s_nop 0
	v_add_f32_e32 v253, 1.0, v253
	v_rcp_f32_e32 v253, v253
	s_nop 0
	v_mul_f32_e32 v252, v252, v253
	ds_write_b32 v213, v252 offset:35840
	s_or_b64 exec, exec, s[0:1]
	s_mul_hi_i32 s0, s48, 0x2aaaaaab
	s_lshr_b32 s1, s0, 31
	s_ashr_i32 s2, s0, 4
	s_add_i32 s2, s2, s1
	s_mul_i32 s0, s2, 0x60
	s_sub_i32 s0, s48, s0
	s_lshl_b32 s0, s0, 5
	s_ashr_i32 s1, s0, 31
	s_mul_i32 s13, s2, 0xc00000
	s_lshl_b64 s[10:11], s[0:1], 2
	s_mul_hi_i32 s12, s2, 0xc00000
	s_add_u32 s10, s13, s10
	s_addc_u32 s11, s12, s11
	v_mov_b32_e32 v1, 0
	v_lshl_add_u64 v[74:75], v[146:147], 0, s[10:11]
	s_mov_b64 s[10:11], 0
	v_mov_b32_e32 v86, v214
	v_mov_b32_e32 v76, 0
	v_mov_b32_e32 v77, v1
	v_mov_b32_e32 v78, 0
	v_mov_b32_e32 v79, v1
	v_mov_b32_e32 v80, 0
	v_mov_b32_e32 v81, v1
	v_mov_b32_e32 v82, 0
	v_mov_b32_e32 v83, v1
	s_waitcnt lgkmcnt(0)
	s_barrier
	v_lshl_add_u64 v[168:169], v[74:75], 0, s[10:11]
	global_load_dword v88, v[168:169], off
	v_add_co_u32_e32 v170, vcc, 0x3000, v168
	s_nop 1
	v_addc_co_u32_e32 v171, vcc, 0, v169, vcc
	global_load_dword v90, v[170:171], off
	v_add_co_u32_e32 v170, vcc, 0x6000, v168
	s_nop 1
	v_addc_co_u32_e32 v171, vcc, 0, v169, vcc
	global_load_dword v92, v[170:171], off
	v_add_co_u32_e32 v170, vcc, 0x9000, v168
	s_nop 1
	v_addc_co_u32_e32 v171, vcc, 0, v169, vcc
	global_load_dword v94, v[170:171], off
	v_add_co_u32_e32 v170, vcc, 0xc000, v168
	s_nop 1
	v_addc_co_u32_e32 v171, vcc, 0, v169, vcc
	global_load_dword v96, v[170:171], off
	v_add_co_u32_e32 v170, vcc, 0xf000, v168
	s_nop 1
	v_addc_co_u32_e32 v171, vcc, 0, v169, vcc
	global_load_dword v98, v[170:171], off
	v_add_co_u32_e32 v170, vcc, 0x12000, v168
	s_nop 1
	v_addc_co_u32_e32 v171, vcc, 0, v169, vcc
	global_load_dword v100, v[170:171], off
	v_add_co_u32_e32 v170, vcc, 0x15000, v168
	s_nop 1
	v_addc_co_u32_e32 v171, vcc, 0, v169, vcc
	global_load_dword v84, v[170:171], off
.LBB0_397:
	v_lshl_add_u64 v[168:169], v[74:75], 0, s[10:11]
	v_add_co_u32_e32 v168, vcc, 0x18000, v168
	s_nop 1
	v_addc_co_u32_e32 v169, vcc, 0, v169, vcc
	ds_read_b128 v[6:9], v86
	ds_read_b128 v[2:5], v86 offset:16
	ds_read_b128 v[10:13], v86 offset:4096
	ds_read_b128 v[14:17], v86 offset:4112
	ds_read_b128 v[50:53], v86 offset:8192
	ds_read_b128 v[38:41], v86 offset:8208
	ds_read_b128 v[22:25], v86 offset:12288
	ds_read_b128 v[18:21], v86 offset:12304
	ds_read_b128 v[58:61], v86 offset:16384
	ds_read_b128 v[46:49], v86 offset:16400
	ds_read_b128 v[34:37], v86 offset:20480
	ds_read_b128 v[26:29], v86 offset:20496
	ds_read_b128 v[62:65], v86 offset:24576
	ds_read_b128 v[54:57], v86 offset:24592
	ds_read_b128 v[42:45], v86 offset:28672
	ds_read_b128 v[30:33], v86 offset:28688
	ds_read_b128 v[66:69], v86 offset:32768
	ds_read_b128 v[70:73], v86 offset:32784
	s_waitcnt lgkmcnt(13)
	v_mov_b32_e32 v102, v50
	v_mov_b32_e32 v103, v10
	s_waitcnt lgkmcnt(9)
	v_mov_b32_e32 v104, v58
	v_mov_b32_e32 v105, v22
	s_waitcnt lgkmcnt(5)
	v_mov_b32_e32 v106, v62
	v_mov_b32_e32 v107, v34
	s_waitcnt lgkmcnt(1)
	v_mov_b32_e32 v108, v66
	v_mov_b32_e32 v109, v42
	v_mov_b32_e32 v10, v51
	v_mov_b32_e32 v22, v59
	v_mov_b32_e32 v34, v63
	v_mov_b32_e32 v42, v67
	v_mov_b32_e32 v50, v52
	v_mov_b32_e32 v51, v12
	v_mov_b32_e32 v58, v60
	v_mov_b32_e32 v59, v24
	v_mov_b32_e32 v62, v64
	v_mov_b32_e32 v63, v36
	v_mov_b32_e32 v66, v68
	v_mov_b32_e32 v67, v44
	v_mov_b32_e32 v12, v53
	v_mov_b32_e32 v24, v61
	v_mov_b32_e32 v36, v65
	v_mov_b32_e32 v44, v69
	v_mov_b32_e32 v52, v38
	v_mov_b32_e32 v53, v14
	v_mov_b32_e32 v60, v46
	v_mov_b32_e32 v61, v18
	v_mov_b32_e32 v64, v54
	v_mov_b32_e32 v65, v26
	s_waitcnt lgkmcnt(0)
	v_mov_b32_e32 v68, v70
	v_mov_b32_e32 v69, v30
	v_mov_b32_e32 v14, v39
	v_mov_b32_e32 v18, v47
	v_mov_b32_e32 v26, v55
	v_mov_b32_e32 v30, v71
	v_mov_b32_e32 v38, v40
	v_mov_b32_e32 v39, v16
	v_mov_b32_e32 v46, v48
	v_mov_b32_e32 v47, v20
	v_mov_b32_e32 v54, v56
	v_mov_b32_e32 v55, v28
	v_mov_b32_e32 v70, v72
	v_mov_b32_e32 v71, v32
	v_mov_b32_e32 v16, v41
	v_mov_b32_e32 v20, v49
	v_mov_b32_e32 v28, v57
	v_mov_b32_e32 v32, v73
	s_add_u32 s10, s10, 0x18000
	s_addc_u32 s11, s11, 0
	v_add_u32_e32 v86, 32, v86
	s_cmp_lg_u32 s10, 0x168000
	s_waitcnt vmcnt(7)
	v_fmac_f32_e32 v1, v88, v6
	v_pk_fma_f32 v[40:41], v[88:89], v[102:103], v[82:83] op_sel_hi:[0,1,1]
	v_pk_fma_f32 v[48:49], v[88:89], v[104:105], v[80:81] op_sel_hi:[0,1,1]
	v_pk_fma_f32 v[56:57], v[88:89], v[106:107], v[78:79] op_sel_hi:[0,1,1]
	v_pk_fma_f32 v[72:73], v[88:89], v[108:109], v[76:77] op_sel_hi:[0,1,1]
	global_load_dword v88, v[168:169], off
	s_waitcnt vmcnt(7)
	v_fmac_f32_e32 v1, v90, v7
	v_pk_fma_f32 v[6:7], v[90:91], v[10:11], v[40:41] op_sel_hi:[0,1,1]
	v_pk_fma_f32 v[10:11], v[90:91], v[22:23], v[48:49] op_sel_hi:[0,1,1]
	v_pk_fma_f32 v[22:23], v[90:91], v[34:35], v[56:57] op_sel_hi:[0,1,1]
	v_pk_fma_f32 v[34:35], v[90:91], v[42:43], v[72:73] op_sel_hi:[0,1,1]
	v_add_co_u32_e32 v170, vcc, 0x3000, v168
	s_nop 1
	v_addc_co_u32_e32 v171, vcc, 0, v169, vcc
	global_load_dword v90, v[170:171], off
	s_waitcnt vmcnt(7)
	v_fmac_f32_e32 v1, v92, v8
	v_pk_fma_f32 v[6:7], v[92:93], v[50:51], v[6:7] op_sel_hi:[0,1,1]
	v_pk_fma_f32 v[10:11], v[92:93], v[58:59], v[10:11] op_sel_hi:[0,1,1]
	v_pk_fma_f32 v[22:23], v[92:93], v[62:63], v[22:23] op_sel_hi:[0,1,1]
	v_pk_fma_f32 v[34:35], v[92:93], v[66:67], v[34:35] op_sel_hi:[0,1,1]
	v_add_co_u32_e32 v170, vcc, 0x6000, v168
	s_nop 1
	v_addc_co_u32_e32 v171, vcc, 0, v169, vcc
	global_load_dword v92, v[170:171], off
	s_waitcnt vmcnt(7)
	v_fmac_f32_e32 v1, v94, v9
	v_pk_fma_f32 v[6:7], v[94:95], v[12:13], v[6:7] op_sel_hi:[0,1,1]
	v_pk_fma_f32 v[8:9], v[94:95], v[24:25], v[10:11] op_sel_hi:[0,1,1]
	v_pk_fma_f32 v[10:11], v[94:95], v[36:37], v[22:23] op_sel_hi:[0,1,1]
	v_pk_fma_f32 v[12:13], v[94:95], v[44:45], v[34:35] op_sel_hi:[0,1,1]
	v_add_co_u32_e32 v170, vcc, 0x9000, v168
	s_nop 1
	v_addc_co_u32_e32 v171, vcc, 0, v169, vcc
	global_load_dword v94, v[170:171], off
	s_waitcnt vmcnt(7)
	v_fmac_f32_e32 v1, v96, v2
	v_pk_fma_f32 v[6:7], v[96:97], v[52:53], v[6:7] op_sel_hi:[0,1,1]
	v_pk_fma_f32 v[8:9], v[96:97], v[60:61], v[8:9] op_sel_hi:[0,1,1]
	v_pk_fma_f32 v[10:11], v[96:97], v[64:65], v[10:11] op_sel_hi:[0,1,1]
	v_pk_fma_f32 v[12:13], v[96:97], v[68:69], v[12:13] op_sel_hi:[0,1,1]
	v_add_co_u32_e32 v170, vcc, 0xc000, v168
	s_nop 1
	v_addc_co_u32_e32 v171, vcc, 0, v169, vcc
	global_load_dword v96, v[170:171], off
	s_waitcnt vmcnt(7)
	v_fmac_f32_e32 v1, v98, v3
	v_pk_fma_f32 v[2:3], v[98:99], v[14:15], v[6:7] op_sel_hi:[0,1,1]
	v_pk_fma_f32 v[6:7], v[98:99], v[18:19], v[8:9] op_sel_hi:[0,1,1]
	v_pk_fma_f32 v[8:9], v[98:99], v[26:27], v[10:11] op_sel_hi:[0,1,1]
	v_pk_fma_f32 v[10:11], v[98:99], v[30:31], v[12:13] op_sel_hi:[0,1,1]
	v_add_co_u32_e32 v170, vcc, 0xf000, v168
	s_nop 1
	v_addc_co_u32_e32 v171, vcc, 0, v169, vcc
	global_load_dword v98, v[170:171], off
	s_waitcnt vmcnt(7)
	v_fmac_f32_e32 v1, v100, v4
	v_pk_fma_f32 v[2:3], v[100:101], v[38:39], v[2:3] op_sel_hi:[0,1,1]
	v_pk_fma_f32 v[6:7], v[100:101], v[46:47], v[6:7] op_sel_hi:[0,1,1]
	v_pk_fma_f32 v[8:9], v[100:101], v[54:55], v[8:9] op_sel_hi:[0,1,1]
	v_pk_fma_f32 v[10:11], v[100:101], v[70:71], v[10:11] op_sel_hi:[0,1,1]
	v_add_co_u32_e32 v170, vcc, 0x12000, v168
	s_nop 1
	v_addc_co_u32_e32 v171, vcc, 0, v169, vcc
	global_load_dword v100, v[170:171], off
	s_waitcnt vmcnt(7)
	v_fmac_f32_e32 v1, v84, v5
	v_pk_fma_f32 v[82:83], v[84:85], v[16:17], v[2:3] op_sel_hi:[0,1,1]
	v_pk_fma_f32 v[80:81], v[84:85], v[20:21], v[6:7] op_sel_hi:[0,1,1]
	v_pk_fma_f32 v[78:79], v[84:85], v[28:29], v[8:9] op_sel_hi:[0,1,1]
	v_pk_fma_f32 v[76:77], v[84:85], v[32:33], v[10:11] op_sel_hi:[0,1,1]
	v_add_co_u32_e32 v170, vcc, 0x15000, v168
	s_nop 1
	v_addc_co_u32_e32 v171, vcc, 0, v169, vcc
	global_load_dword v84, v[170:171], off
	s_cbranch_scc1 .LBB0_397
	ds_read_b128 v[6:9], v86
	ds_read_b128 v[2:5], v86 offset:16
	ds_read_b128 v[10:13], v86 offset:4096
	ds_read_b128 v[14:17], v86 offset:4112
	ds_read_b128 v[50:53], v86 offset:8192
	ds_read_b128 v[38:41], v86 offset:8208
	ds_read_b128 v[22:25], v86 offset:12288
	ds_read_b128 v[18:21], v86 offset:12304
	ds_read_b128 v[58:61], v86 offset:16384
	ds_read_b128 v[46:49], v86 offset:16400
	ds_read_b128 v[34:37], v86 offset:20480
	ds_read_b128 v[26:29], v86 offset:20496
	ds_read_b128 v[62:65], v86 offset:24576
	ds_read_b128 v[54:57], v86 offset:24592
	ds_read_b128 v[42:45], v86 offset:28672
	ds_read_b128 v[30:33], v86 offset:28688
	ds_read_b128 v[66:69], v86 offset:32768
	ds_read_b128 v[70:73], v86 offset:32784
	s_waitcnt lgkmcnt(13)
	v_mov_b32_e32 v102, v50
	v_mov_b32_e32 v103, v10
	s_waitcnt lgkmcnt(9)
	v_mov_b32_e32 v104, v58
	v_mov_b32_e32 v105, v22
	s_waitcnt lgkmcnt(5)
	v_mov_b32_e32 v106, v62
	v_mov_b32_e32 v107, v34
	s_waitcnt lgkmcnt(1)
	v_mov_b32_e32 v108, v66
	v_mov_b32_e32 v109, v42
	v_mov_b32_e32 v10, v51
	v_mov_b32_e32 v22, v59
	v_mov_b32_e32 v34, v63
	v_mov_b32_e32 v42, v67
	v_mov_b32_e32 v50, v52
	v_mov_b32_e32 v51, v12
	v_mov_b32_e32 v58, v60
	v_mov_b32_e32 v59, v24
	v_mov_b32_e32 v62, v64
	v_mov_b32_e32 v63, v36
	v_mov_b32_e32 v66, v68
	v_mov_b32_e32 v67, v44
	v_mov_b32_e32 v12, v53
	v_mov_b32_e32 v24, v61
	v_mov_b32_e32 v36, v65
	v_mov_b32_e32 v44, v69
	v_mov_b32_e32 v52, v38
	v_mov_b32_e32 v53, v14
	v_mov_b32_e32 v60, v46
	v_mov_b32_e32 v61, v18
	v_mov_b32_e32 v64, v54
	v_mov_b32_e32 v65, v26
	s_waitcnt lgkmcnt(0)
	v_mov_b32_e32 v68, v70
	v_mov_b32_e32 v69, v30
	v_mov_b32_e32 v14, v39
	v_mov_b32_e32 v18, v47
	v_mov_b32_e32 v26, v55
	v_mov_b32_e32 v30, v71
	v_mov_b32_e32 v38, v40
	v_mov_b32_e32 v39, v16
	v_mov_b32_e32 v46, v48
	v_mov_b32_e32 v47, v20
	v_mov_b32_e32 v54, v56
	v_mov_b32_e32 v55, v28
	v_mov_b32_e32 v70, v72
	v_mov_b32_e32 v71, v32
	v_mov_b32_e32 v16, v41
	v_mov_b32_e32 v20, v49
	v_mov_b32_e32 v28, v57
	v_mov_b32_e32 v32, v73
	s_add_u32 s10, s10, 0x18000
	s_addc_u32 s11, s11, 0
	v_add_u32_e32 v86, 32, v86
	s_waitcnt vmcnt(7)
	v_fmac_f32_e32 v1, v88, v6
	v_pk_fma_f32 v[40:41], v[88:89], v[102:103], v[82:83] op_sel_hi:[0,1,1]
	v_pk_fma_f32 v[48:49], v[88:89], v[104:105], v[80:81] op_sel_hi:[0,1,1]
	v_pk_fma_f32 v[56:57], v[88:89], v[106:107], v[78:79] op_sel_hi:[0,1,1]
	v_pk_fma_f32 v[72:73], v[88:89], v[108:109], v[76:77] op_sel_hi:[0,1,1]
	s_waitcnt vmcnt(6)
	v_fmac_f32_e32 v1, v90, v7
	v_pk_fma_f32 v[6:7], v[90:91], v[10:11], v[40:41] op_sel_hi:[0,1,1]
	v_pk_fma_f32 v[10:11], v[90:91], v[22:23], v[48:49] op_sel_hi:[0,1,1]
	v_pk_fma_f32 v[22:23], v[90:91], v[34:35], v[56:57] op_sel_hi:[0,1,1]
	v_pk_fma_f32 v[34:35], v[90:91], v[42:43], v[72:73] op_sel_hi:[0,1,1]
	s_waitcnt vmcnt(5)
	v_fmac_f32_e32 v1, v92, v8
	v_pk_fma_f32 v[6:7], v[92:93], v[50:51], v[6:7] op_sel_hi:[0,1,1]
	v_pk_fma_f32 v[10:11], v[92:93], v[58:59], v[10:11] op_sel_hi:[0,1,1]
	v_pk_fma_f32 v[22:23], v[92:93], v[62:63], v[22:23] op_sel_hi:[0,1,1]
	v_pk_fma_f32 v[34:35], v[92:93], v[66:67], v[34:35] op_sel_hi:[0,1,1]
	s_waitcnt vmcnt(4)
	v_fmac_f32_e32 v1, v94, v9
	v_pk_fma_f32 v[6:7], v[94:95], v[12:13], v[6:7] op_sel_hi:[0,1,1]
	v_pk_fma_f32 v[8:9], v[94:95], v[24:25], v[10:11] op_sel_hi:[0,1,1]
	v_pk_fma_f32 v[10:11], v[94:95], v[36:37], v[22:23] op_sel_hi:[0,1,1]
	v_pk_fma_f32 v[12:13], v[94:95], v[44:45], v[34:35] op_sel_hi:[0,1,1]
	s_waitcnt vmcnt(3)
	v_fmac_f32_e32 v1, v96, v2
	v_pk_fma_f32 v[6:7], v[96:97], v[52:53], v[6:7] op_sel_hi:[0,1,1]
	v_pk_fma_f32 v[8:9], v[96:97], v[60:61], v[8:9] op_sel_hi:[0,1,1]
	v_pk_fma_f32 v[10:11], v[96:97], v[64:65], v[10:11] op_sel_hi:[0,1,1]
	v_pk_fma_f32 v[12:13], v[96:97], v[68:69], v[12:13] op_sel_hi:[0,1,1]
	s_waitcnt vmcnt(2)
	v_fmac_f32_e32 v1, v98, v3
	v_pk_fma_f32 v[2:3], v[98:99], v[14:15], v[6:7] op_sel_hi:[0,1,1]
	v_pk_fma_f32 v[6:7], v[98:99], v[18:19], v[8:9] op_sel_hi:[0,1,1]
	v_pk_fma_f32 v[8:9], v[98:99], v[26:27], v[10:11] op_sel_hi:[0,1,1]
	v_pk_fma_f32 v[10:11], v[98:99], v[30:31], v[12:13] op_sel_hi:[0,1,1]
	s_waitcnt vmcnt(1)
	v_fmac_f32_e32 v1, v100, v4
	v_pk_fma_f32 v[2:3], v[100:101], v[38:39], v[2:3] op_sel_hi:[0,1,1]
	v_pk_fma_f32 v[6:7], v[100:101], v[46:47], v[6:7] op_sel_hi:[0,1,1]
	v_pk_fma_f32 v[8:9], v[100:101], v[54:55], v[8:9] op_sel_hi:[0,1,1]
	v_pk_fma_f32 v[10:11], v[100:101], v[70:71], v[10:11] op_sel_hi:[0,1,1]
	s_waitcnt vmcnt(0)
	v_fmac_f32_e32 v1, v84, v5
	v_pk_fma_f32 v[82:83], v[84:85], v[16:17], v[2:3] op_sel_hi:[0,1,1]
	v_pk_fma_f32 v[80:81], v[84:85], v[20:21], v[6:7] op_sel_hi:[0,1,1]
	v_pk_fma_f32 v[78:79], v[84:85], v[28:29], v[8:9] op_sel_hi:[0,1,1]
	v_pk_fma_f32 v[76:77], v[84:85], v[32:33], v[10:11] op_sel_hi:[0,1,1]
	v_add_u32_e32 v2, 0x9000, v221
	ds_write2_b32 v2, v1, v83 offset1:32
	ds_write2_b32 v2, v82, v81 offset0:64 offset1:96
	ds_write2_b32 v2, v80, v79 offset0:128 offset1:160
	ds_write2_b32 v2, v78, v77 offset0:192 offset1:224
	ds_write_b32 v221, v76 offset:37888
	s_waitcnt lgkmcnt(0)
	s_barrier
	s_mov_b64 s[10:11], exec
	v_readlane_b32 s12, v247, 47
	v_readlane_b32 s13, v247, 48
	s_and_b64 s[12:13], s[10:11], s[12:13]
	s_mov_b64 exec, s[12:13]
	s_cbranch_execz .LBB0_352
	s_mul_i32 s1, s2, 0xc00
	v_readlane_b32 s52, v246, 5
	s_add_i32 s1, s1, s0
	v_readlane_b32 s64, v246, 17
	v_readlane_b32 s65, v246, 18
	v_readlane_b32 s66, v246, 19
	v_readlane_b32 s67, v246, 20
	v_or_b32_e32 v2, s1, v195
	v_readlane_b32 s64, v247, 53
	s_mulk_i32 s2, 0x6000
	s_lshl_b32 s0, s48, 5
	v_ashrrev_i32_e32 v3, 31, v2
	v_readlane_b32 s53, v246, 6
	v_readlane_b32 s72, v247, 61
	s_add_i32 s0, s0, s2
	v_readlane_b32 s65, v247, 54
	v_readlane_b32 s66, v247, 55
	v_readlane_b32 s67, v247, 56
	v_readlane_b32 s68, v247, 57
	v_readlane_b32 s69, v247, 58
	v_readlane_b32 s70, v247, 59
	v_readlane_b32 s71, v247, 60
	v_readlane_b32 s74, v247, 63
	v_readlane_b32 s75, v246, 0
	v_readlane_b32 s76, v246, 1
	v_readlane_b32 s77, v246, 2
	v_readlane_b32 s78, v246, 3
	v_readlane_b32 s79, v246, 4
	v_readlane_b32 s72, v246, 60
	v_lshl_add_u64 v[2:3], v[2:3], 2, s[52:53]
	v_add_u32_e32 v4, s0, v216
	s_mov_b64 s[0:1], 0
	v_mov_b32_e32 v1, v217
	v_mov_b32_e32 v6, v215
	v_readlane_b32 s54, v246, 7
	v_readlane_b32 s55, v246, 8
	v_readlane_b32 s56, v246, 9
	v_readlane_b32 s57, v246, 10
	v_readlane_b32 s58, v246, 11
	v_readlane_b32 s59, v246, 12
	v_readlane_b32 s60, v246, 13
	v_readlane_b32 s61, v246, 14
	v_readlane_b32 s62, v246, 15
	v_readlane_b32 s63, v246, 16
	v_readlane_b32 s73, v247, 62
